# v19 + out-proj fused epilogue: redundant L1 invalidate before the sc1 slot loads removed (2 per layer)
# speedup vs baseline: 1.0110x; 1.0110x over previous
.LBB0_598:
	s_waitcnt vmcnt(0) lgkmcnt(0)
.LBB0_599:
	s_waitcnt vmcnt(0) lgkmcnt(0)
	s_barrier
	s_lshl_b32 s26, s19, 8
	s_and_saveexec_b64 s[22:23], s[30:31]
	s_cbranch_execz .LBB0_601
	v_add_u32_e32 v128, s26, v238
	v_ashrrev_i32_e32 v129, 31, v128
	v_lshlrev_b64 v[128:129], 5, v[128:129]
	v_lshl_add_u64 v[136:137], s[4:5], 0, v[128:129]
	global_load_dwordx4 v[128:131], v[136:137], off sc1
	global_load_dwordx4 v[132:135], v[136:137], off offset:16 sc1
	s_waitcnt vmcnt(0)
	s_mov_b32 s4, 0xf800000
	v_mov_b32_e32 v136, v128
	v_mov_b32_e32 v137, v132
	v_mov_b32_e32 v132, v129
	v_pk_add_f32 v[128:129], v[136:137], v[132:133]
	v_mov_b32_e32 v132, v130
	v_mov_b32_e32 v133, v134
	v_mov_b32_e32 v134, v131
	v_pk_add_f32 v[130:131], v[132:133], v[134:135]
	s_nop 0
	v_pk_add_f32 v[128:129], v[128:129], v[130:131]
	s_nop 0
	v_add_f32_e32 v128, v128, v129
	v_fmamk_f32 v128, v128, 0x3a000000, v231
	v_cmp_gt_f32_e32 vcc, s4, v128
	v_mul_f32_e32 v129, 0x4f800000, v128
	s_nop 0
	v_cndmask_b32_e32 v128, v128, v129, vcc
	v_sqrt_f32_e32 v129, v128
	s_nop 0
	v_add_u32_e32 v130, -1, v129
	v_fma_f32 v131, -v130, v129, v128
	v_cmp_ge_f32_e64 s[40:41], 0, v131
	v_add_u32_e32 v131, 1, v129
	s_nop 0
	v_cndmask_b32_e64 v130, v129, v130, s[40:41]
	v_fma_f32 v129, -v131, v129, v128
	v_cmp_lt_f32_e64 s[40:41], 0, v129
	s_nop 1
	v_cndmask_b32_e64 v129, v130, v131, s[40:41]
	v_mul_f32_e32 v130, 0x37800000, v129
	v_cndmask_b32_e32 v129, v129, v130, vcc
	v_cmp_class_f32_e32 vcc, v128, v232
	s_nop 1
	v_cndmask_b32_e32 v128, v129, v128, vcc
	v_div_scale_f32 v129, s[4:5], v128, v128, 1.0
	v_rcp_f32_e32 v130, v129
	s_nop 0
	v_fma_f32 v131, -v129, v130, 1.0
	v_fmac_f32_e32 v130, v131, v130
	v_div_scale_f32 v131, vcc, 1.0, v128, 1.0
	v_mul_f32_e32 v132, v131, v130
	v_fma_f32 v133, -v129, v132, v131
	v_fmac_f32_e32 v132, v133, v130
	v_fma_f32 v129, -v129, v132, v131
	v_div_fmas_f32 v129, v129, v130, v132
	v_div_fixup_f32 v128, v129, v128, 1.0
	v_lshl_add_u32 v129, v238, 2, 0
	ds_write_b32 v129, v128 offset:4096

.LBB0_700:
	s_waitcnt vmcnt(0) lgkmcnt(0)
.LBB0_701:
	s_waitcnt vmcnt(0) lgkmcnt(0)
	s_barrier
	s_and_saveexec_b64 s[12:13], s[30:31]
	s_cbranch_execz .LBB0_703
	v_add_u32_e32 v128, s26, v238
	v_ashrrev_i32_e32 v129, 31, v128
	v_lshlrev_b64 v[128:129], 5, v[128:129]
	v_lshl_add_u64 v[136:137], s[4:5], 0, v[128:129]
	global_load_dwordx4 v[128:131], v[136:137], off sc1
	global_load_dwordx4 v[132:135], v[136:137], off offset:16 sc1
	s_waitcnt vmcnt(0)
	s_mov_b32 s4, 0xf800000
	v_mov_b32_e32 v136, v128
	v_mov_b32_e32 v137, v132
	v_mov_b32_e32 v132, v129
	v_pk_add_f32 v[128:129], v[136:137], v[132:133]
	v_mov_b32_e32 v132, v130
	v_mov_b32_e32 v133, v134
	v_mov_b32_e32 v134, v131
	v_pk_add_f32 v[130:131], v[132:133], v[134:135]
	s_nop 0
	v_pk_add_f32 v[128:129], v[128:129], v[130:131]
	s_nop 0
	v_add_f32_e32 v128, v128, v129
	v_fmamk_f32 v128, v128, 0x3a000000, v231
	v_cmp_gt_f32_e32 vcc, s4, v128
	v_mul_f32_e32 v129, 0x4f800000, v128
	s_nop 0
	v_cndmask_b32_e32 v128, v128, v129, vcc
	v_sqrt_f32_e32 v129, v128
	s_nop 0
	v_add_u32_e32 v130, -1, v129
	v_fma_f32 v131, -v130, v129, v128
	v_cmp_ge_f32_e64 s[34:35], 0, v131
	v_add_u32_e32 v131, 1, v129
	s_nop 0
	v_cndmask_b32_e64 v130, v129, v130, s[34:35]
	v_fma_f32 v129, -v131, v129, v128
	v_cmp_lt_f32_e64 s[34:35], 0, v129
	s_nop 1
	v_cndmask_b32_e64 v129, v130, v131, s[34:35]
	v_mul_f32_e32 v130, 0x37800000, v129
	v_cndmask_b32_e32 v129, v129, v130, vcc
	v_cmp_class_f32_e32 vcc, v128, v232
	s_nop 1
	v_cndmask_b32_e32 v128, v129, v128, vcc
	v_div_scale_f32 v129, s[4:5], v128, v128, 1.0
	v_rcp_f32_e32 v130, v129
	s_nop 0
	v_fma_f32 v131, -v129, v130, 1.0
	v_fmac_f32_e32 v130, v131, v130
	v_div_scale_f32 v131, vcc, 1.0, v128, 1.0
	v_mul_f32_e32 v132, v131, v130
	v_fma_f32 v133, -v129, v132, v131
	v_fmac_f32_e32 v132, v133, v130
	v_fma_f32 v129, -v129, v132, v131
	v_div_fmas_f32 v129, v129, v130, v132
	v_div_fixup_f32 v128, v129, v128, 1.0
	v_lshl_add_u32 v129, v238, 2, 0
	ds_write_b32 v129, v128 offset:4096
